# seam 0: cooperative-groups grid sync replaced by the same two-level XCD barrier the other seams use (on top of packed-f32 RWKV scan)
# speedup vs baseline: 1.0157x; 1.0157x over previous
.LBB0_228:
	s_cmp_lt_i32 s43, 2
	s_cbranch_scc1 .LBB0_240
	s_add_u32 s10, s88, 0x160
	s_addc_u32 s11, s89, 0
	s_load_dword s0, s[88:89], 0x160
	s_waitcnt lgkmcnt(0)
	s_waitcnt vmcnt(0)
	s_barrier
	s_and_saveexec_b64 s[4:5], s[86:87]
	s_cbranch_execz .Lxb0_310
	s_add_i32 s1, 0, 0x23fc0
	v_mov_b32_e32 v0, s1
	s_waitcnt vmcnt(0) expcnt(0) lgkmcnt(0)
	ds_read_b32 v2, v0
	s_add_i32 s1, 0, 0x23fc4
	v_mov_b32_e32 v0, s1
	ds_read_b32 v0, v0
	s_waitcnt lgkmcnt(1)
	v_cmp_ne_u32_e32 vcc, 0, v2
	s_cbranch_vccnz .Lxb0_274
	s_add_u32 s6, s40, 0x1000
	s_load_dwordx2 s[2:3], s[10:11], 0x4
	s_addc_u32 s7, s41, 0
	s_add_u32 s8, s40, 0x1100
	s_addc_u32 s9, s41, 0
	s_add_u32 s10, s40, 0x1200
	s_addc_u32 s11, s41, 0
	s_waitcnt lgkmcnt(0)
	s_mul_i32 s0, s2, s0
	s_add_u32 s12, s40, 0x1300
	s_mul_i32 s0, s0, s3
	s_addc_u32 s13, s41, 0
	s_mov_b32 s1, 1
	v_mov_b32_e32 v16, 0
	s_branch .Lxb0_262

.Lxb0_262:
	global_load_dword v15, v16, s[40:41] offset:1024 sc1
	global_load_dword v0, v16, s[40:41] offset:1280 sc1
	global_load_dword v1, v16, s[40:41] offset:1536 sc1
	global_load_dword v2, v16, s[40:41] offset:1792 sc1
	global_load_dword v3, v16, s[40:41] offset:2048 sc1
	global_load_dword v4, v16, s[40:41] offset:2304 sc1
	global_load_dword v5, v16, s[40:41] offset:2560 sc1
	global_load_dword v6, v16, s[40:41] offset:2816 sc1
	global_load_dword v7, v16, s[40:41] offset:3072 sc1
	global_load_dword v8, v16, s[40:41] offset:3328 sc1
	global_load_dword v9, v16, s[40:41] offset:3584 sc1
	global_load_dword v10, v16, s[40:41] offset:3840 sc1
	global_load_dword v11, v16, s[6:7] sc1
	global_load_dword v12, v16, s[8:9] sc1
	global_load_dword v13, v16, s[10:11] sc1
	global_load_dword v14, v16, s[12:13] sc1
	s_mov_b64 s[14:15], -1
	s_mov_b64 s[16:17], -1
	s_waitcnt vmcnt(14)
	v_add_u32_e32 v17, v0, v15
	s_waitcnt vmcnt(13)
	v_add_u32_e32 v17, v17, v1
	s_waitcnt vmcnt(12)
	v_add_u32_e32 v17, v17, v2
	s_waitcnt vmcnt(11)
	v_add_u32_e32 v17, v17, v3
	s_waitcnt vmcnt(10)
	v_add_u32_e32 v17, v17, v4
	s_waitcnt vmcnt(9)
	v_add_u32_e32 v17, v17, v5
	s_waitcnt vmcnt(8)
	v_add_u32_e32 v17, v17, v6
	s_waitcnt vmcnt(7)
	v_add_u32_e32 v17, v17, v7
	s_waitcnt vmcnt(6)
	v_add_u32_e32 v17, v17, v8
	s_waitcnt vmcnt(5)
	v_add_u32_e32 v17, v17, v9
	s_waitcnt vmcnt(4)
	v_add_u32_e32 v17, v17, v10
	s_waitcnt vmcnt(3)
	v_add_u32_e32 v17, v17, v11
	s_waitcnt vmcnt(2)
	v_add_u32_e32 v17, v17, v12
	s_waitcnt vmcnt(1)
	v_add_u32_e32 v17, v17, v13
	s_waitcnt vmcnt(0)
	v_add_u32_e32 v17, v17, v14
	v_cmp_eq_u32_e32 vcc, s0, v17
	s_cbranch_vccnz .Lxb0_261

	s_and_b32 s2, s1, 0xff
	s_cmp_eq_u32 s2, 0
	s_mov_b64 s[18:19], -1
	s_sleep 1
	s_cbranch_scc1 .Lxb0_266

	s_and_b64 vcc, exec, s[18:19]
	s_cbranch_vccz .Lxb0_261

.Lxb0_266:
	global_load_dword v17, v16, s[40:41] offset:512 sc1
	s_waitcnt vmcnt(0)
	v_cmp_eq_u32_e32 vcc, 0, v17
	s_cbranch_vccnz .Lxb0_268

	s_branch .Lxb0_261

.Lxb0_280:
	s_and_b32 s1, s0, 0xff
	s_mov_b64 s[18:19], -1
	s_cmp_lg_u32 s1, 0
	s_mov_b64 s[22:23], -1
	s_sleep 1
	s_cbranch_scc0 .Lxb0_283

	s_and_b64 vcc, exec, s[22:23]
	s_cbranch_vccz .Lxb0_279

.Lxb0_283:
	global_load_dword v2, v0, s[40:41] offset:512 sc1
	s_waitcnt vmcnt(0)
	v_cmp_eq_u32_e32 vcc, 0, v2
	s_cbranch_vccnz .Lxb0_285

	s_mov_b64 s[20:21], -1
	s_branch .Lxb0_279

.Lxb0_297:
	s_and_b32 s1, s0, 0xff
	s_cmp_lg_u32 s1, 0
	s_mov_b64 s[22:23], -1
	s_sleep 1
	s_cbranch_scc0 .Lxb0_300

	s_mov_b64 s[24:25], -1
	s_and_b64 vcc, exec, s[22:23]
	s_cbranch_vccz .Lxb0_296

.Lxb0_300:
	global_load_dword v1, v0, s[12:13] sc1
	s_waitcnt vmcnt(0)
	v_cmp_eq_u32_e32 vcc, 0, v1
	s_cbranch_vccnz .Lxb0_302

	s_mov_b64 s[20:21], -1
	s_mov_b64 s[24:25], -1
	s_branch .Lxb0_296

.Lxb0_310:
	s_or_b64 exec, exec, s[4:5]
	s_waitcnt lgkmcnt(0)
	s_barrier
.LBB0_240:
	s_cmp_lt_i32 s42, 2
	s_cselect_b64 s[0:1], -1, 0
	s_cmp_gt_i32 s43, 1
	s_cselect_b64 s[2:3], -1, 0
	s_and_b64 s[0:1], s[0:1], s[2:3]
	s_andn2_b64 vcc, exec, s[0:1]
	s_cbranch_vccnz .LBB0_311
	v_mbcnt_hi_u32_b32 v8, -1, v210
	v_add_u32_e32 v9, s91, v8
	s_load_dword s0, s[88:89], 0x160
	s_add_u32 s10, s88, 0x160
	s_mov_b32 s1, s90
	s_addc_u32 s11, s89, 0
	s_mov_b64 s[4:5], s[88:89]
	s_waitcnt lgkmcnt(0)
	s_mov_b32 s2, s0
	s_cmpk_gt_i32 s1, 0x57f
	v_readfirstlane_b32 s19, v9
	s_cbranch_scc1 .LBB0_257
	v_lshlrev_b32_e32 v0, 4, v9
	v_add_u32_e32 v1, 0x2000, v0
	v_ashrrev_i32_e32 v2, 31, v1
	v_lshrrev_b32_e32 v2, 22, v2
	v_add_u32_e32 v2, v1, v2
	v_ashrrev_i32_e32 v10, 10, v2
	v_mul_i32_i24_e32 v2, 0x400, v10
	v_sub_u32_e32 v1, v1, v2
	v_lshrrev_b32_e32 v2, 4, v1
	v_bitop3_b32 v1, v2, v1, 32 bitop3:0x6c
	v_ashrrev_i32_e32 v2, 31, v1
	v_lshrrev_b32_e32 v2, 26, v2
	v_add_u32_e32 v2, v1, v2
	v_lshlrev_b32_e32 v3, 3, v10
	v_ashrrev_i32_e32 v11, 6, v2
	v_and_b32_e32 v3, -16, v3
	v_add_u32_e32 v3, v11, v3
	v_and_b32_e32 v4, 3, v11
	s_mov_b32 s6, 0x1fffe0
	v_lshrrev_b32_e32 v5, 2, v3
	v_lshlrev_b32_e32 v6, 1, v3
	v_and_b32_e32 v2, 0xc0, v2
	v_and_or_b32 v4, v3, s6, v4
	v_and_b32_e32 v5, 4, v5
	v_and_b32_e32 v6, 24, v6
	v_sub_u32_e32 v1, v1, v2
	v_mov_b32_e32 v2, 1
	v_or3_b32 v4, v4, v5, v6
	v_lshlrev_b32_e32 v5, 5, v10
	v_ashrrev_i16_sdwa v1, v2, sext(v1) dst_sel:DWORD dst_unused:UNUSED_PAD src0_sel:DWORD src1_sel:BYTE_0
	v_and_b32_e32 v5, 32, v5
	v_bfe_i32 v12, v1, 0, 16
	v_add_lshl_u32 v1, v5, v12, 1
	v_lshl_add_u32 v128, v4, 11, v1
	v_lshl_add_u32 v130, v3, 11, v1
	v_bfe_i32 v1, v9, 27, 1
	v_lshrrev_b32_e32 v1, 22, v1
	v_add_u32_e32 v1, v0, v1
	s_load_dwordx2 s[4:5], s[4:5], 0x150
	v_and_b32_e32 v1, 0xfffffc00, v1
	v_sub_u32_e32 v0, v0, v1
	v_lshrrev_b32_e32 v1, 4, v0
	v_ashrrev_i32_e32 v3, 31, v9
	v_bitop3_b32 v0, v1, v0, 32 bitop3:0x6c
	v_lshrrev_b32_e32 v3, 26, v3
	v_ashrrev_i32_e32 v1, 31, v0
	v_add_u32_e32 v3, v9, v3
	s_waitcnt lgkmcnt(0)
	s_add_u32 s3, s4, 0x2200000
	v_lshrrev_b32_e32 v1, 26, v1
	v_ashrrev_i32_e32 v14, 6, v3
	s_addc_u32 s21, s5, 0
	v_add_u32_e32 v1, v0, v1
	v_lshlrev_b32_e32 v3, 3, v14
	s_add_u32 s23, s4, 0x400000
	v_ashrrev_i32_e32 v13, 6, v1
	v_and_b32_e32 v3, -16, v3
	s_addc_u32 s33, s5, 0
	v_add_u32_e32 v3, v13, v3
	v_and_b32_e32 v4, 3, v13
	s_ashr_i32 s37, s1, 31
	v_and_or_b32 v4, v3, s6, v4
	s_lshr_b32 s6, s37, 29
	s_add_i32 s6, s1, s6
	s_ashr_i32 s16, s19, 6
	s_ashr_i32 s7, s6, 3
	s_and_b32 s6, s6, -8
	s_ashr_i32 s20, s19, 8
	s_lshl_b32 s36, s16, 10
	s_sub_i32 s6, s1, s6
	s_cmp_lt_i32 s6, 0
	s_movk_i32 s44, 0xb1
	s_cselect_b32 s8, s44, 0xb0
	s_mul_i32 s6, s8, s6
	s_add_i32 s6, s6, s7
	s_mul_hi_i32 s7, s6, 0x2e8ba2e9
	s_lshr_b32 s8, s7, 31
	s_ashr_i32 s7, s7, 5
	s_add_i32 s7, s7, s8
	s_lshl_b32 s8, s7, 3
	s_mulk_i32 s7, 0xb0
	s_sub_i32 s6, s6, s7
	s_bfe_u32 s7, s6, 0x3001c
	s_add_i32 s7, s6, s7
	s_sext_i32_i16 s9, s7
	s_and_b32 s7, s7, 0xfff8
	s_sub_i32 s6, s6, s7
	s_sext_i32_i16 s6, s6
	v_lshrrev_b32_e32 v5, 2, v3
	v_lshlrev_b32_e32 v6, 1, v3
	v_and_b32_e32 v1, 0xc0, v1
	s_lshr_b32 s18, s9, 3
	s_add_i32 s6, s8, s6
	v_and_b32_e32 v5, 4, v5
	v_and_b32_e32 v6, 24, v6
	v_sub_u32_e32 v0, v0, v1
	s_ashr_i32 s7, s6, 31
	s_bfe_i64 s[8:9], s[18:19], 0x100000
	v_or3_b32 v4, v4, v5, v6
	v_lshlrev_b32_e32 v5, 5, v14
	v_ashrrev_i16_sdwa v0, v2, sext(v0) dst_sel:DWORD dst_unused:UNUSED_PAD src0_sel:DWORD src1_sel:BYTE_0
	s_lshl_b64 s[12:13], s[6:7], 19
	s_lshl_b64 s[8:9], s[8:9], 19
	v_and_b32_e32 v5, 32, v5
	v_bfe_i32 v15, v0, 0, 16
	s_add_u32 s8, s23, s8
	v_add_lshl_u32 v0, v5, v15, 1
	s_addc_u32 s9, s33, s9
	s_add_i32 s45, s36, 0
	v_lshl_add_u32 v132, v4, 11, v0
	s_add_i32 m0, s45, 0x10000
	v_lshl_add_u32 v134, v3, 11, v0
	global_load_lds_dwordx4 v132, s[8:9]
	s_add_i32 m0, s45, 0x12000
	s_add_u32 s14, s8, 0x40000
	global_load_lds_dwordx4 v128, s[8:9]
	s_addc_u32 s15, s9, 0
	s_add_i32 m0, s45, 0x14000
	v_mov_b32_e32 v133, 0
	global_load_lds_dwordx4 v132, s[14:15]
	s_add_i32 m0, s45, 0x16000
	s_add_u32 s34, s3, s12
	s_addc_u32 s35, s21, s13
	s_add_i32 s46, s45, 0x2000
	global_load_lds_dwordx4 v128, s[14:15]
	s_mov_b32 m0, s45
	s_add_u32 s12, s34, 0x40000
	global_load_lds_dwordx4 v134, s[34:35]
	s_mov_b32 m0, s46
	s_addc_u32 s13, s35, 0
	s_add_i32 s47, s45, 0x4000
	global_load_lds_dwordx4 v130, s[34:35]
	s_mov_b32 m0, s47
	s_add_i32 s48, s45, 0x6000
	global_load_lds_dwordx4 v134, s[12:13]
	s_mov_b32 m0, s48
	v_mov_b32_e32 v129, v133
	global_load_lds_dwordx4 v130, s[12:13]
	v_mov_b32_e32 v135, v133
	v_mov_b32_e32 v131, v133
	s_cmp_eq_u32 s20, 1
	v_lshl_add_u64 v[6:7], s[8:9], 0, v[132:133]
	v_lshl_add_u64 v[4:5], s[8:9], 0, v[128:129]
	v_lshl_add_u64 v[0:1], s[34:35], 0, v[134:135]
	s_cselect_b64 s[12:13], -1, 0
	s_cmp_lg_u32 s20, 1
	v_lshl_add_u64 v[2:3], s[34:35], 0, v[130:131]
	s_cbranch_scc1 .LBB0_244
	s_barrier
